# K-rope epilogue: rope-register protection waits (second-half rope use, address-pair reuse) relaxed to counted waits that leave the group's own stores in flight
# baseline (speedup 1.0000x reference)
; DI void st8f_nt(float* p, const float (&v)[8]) { __builtin_nontemporal_store((v4f){v[0], v[1], v[2], v[3]}, (v4f*)p); __builtin_nontemporal_store((v4f){v[4], v[5], v[6], v[7]}, (v4f*)(p + 4)); }
;     template <int MODE>
;     DI void rows(const pg8::f32x4 (&acc)[2][2][4][2], const pg8::Unit& u, int wr, int wc, int fr, int fq) const {
;     ...
;                     const int col = pn * 256 + bj * 128 + tc0;
;                     if constexpr (MODE <= 1) {
;                         if ((wc & 1) == 0) {
;                             const float sgn = fq == 0 ? -1.f : 1.f;
; #pragma unroll
;                             for (int i = 0; i < 8; ++i) { const float pr = __shfl_xor(v[i], 16); const float r = v[i] * cs[i].x + sgn * pr * cs[i].y; v[i] = fq < 2 ? r : v[i]; }
;                         }
;                         if constexpr (MODE == 0) {
; #pragma unroll
;                             for (int i = 0; i < 8; ++i) v[i] *= QA_SCALE;
;                         }
;                     }
;                     if constexpr (MODE == 1 || MODE == 2) {
;                         const int cs1 = (pn & 3) * 256 + bj * 128 + tc0;
;                         float* dst = row < MP ? out + (MODE == 1 ? O_KP : O_VP) + (size_t)row * 1024 + cs1 : out + (MODE == 1 ? O_KS : O_VS) + (size_t)(row - MP) * 1024 + cs1;
;                         st8f_nt(dst, v);
;     ...
;                     } else if constexpr (MODE == 1 || MODE == 2) {
;                         if (row < MP) {
;                             const int cc = (pn & 3) * 256 + bj * 128 + tc0, hd = cc >> 7;
;                             st8bf((MODE == 1 ? KC : VC) + ((size_t)((row >> 12) * 8 + hd) * SEQ + (row & (SEQ - 1))) * 128 + (cc & 127), v);
;                         } else st8bf(P + (size_t)row * PLD + col, v);
.LBB0_406:
	v_and_b32_e32 v131, 64, v216
	v_xor_b32_e32 v130, 16, v216
	v_add_u32_e32 v131, 64, v131
	v_cmp_lt_i32_e32 vcc, v130, v131
	s_waitcnt vmcnt(7)
	v_mov_b32_e32 v131, v151
	v_mov_b32_e32 v133, v153
	v_cndmask_b32_e32 v130, v216, v130, vcc
	v_lshlrev_b32_e32 v177, 2, v130
	ds_bpermute_b32 v130, v177, v114
	v_mov_b32_e32 v135, v149
	v_mov_b32_e32 v137, v145
	s_waitcnt lgkmcnt(0)
	v_cndmask_b32_e64 v132, v130, -v130, s[0:1]
	v_mov_b32_e32 v130, v114
	v_mov_b32_e32 v151, v132
	v_pk_mul_f32 v[130:131], v[130:131], v[150:151]
	v_mov_b32_e32 v132, v115
	v_add_f32_e32 v130, v130, v131
	ds_bpermute_b32 v131, v177, v115
	v_cndmask_b32_e64 v130, v114, v130, s[10:11]
	v_mov_b32_e32 v224, v130
	s_waitcnt lgkmcnt(0)
	v_cndmask_b32_e64 v131, v131, -v131, s[0:1]
	v_mov_b32_e32 v153, v131
	v_pk_mul_f32 v[132:133], v[132:133], v[152:153]
	s_nop 0
	v_add_f32_e32 v131, v132, v133
	ds_bpermute_b32 v132, v177, v116
	v_mov_b32_e32 v133, v147
	v_cndmask_b32_e64 v131, v115, v131, s[10:11]
	v_mov_b32_e32 v225, v131
	s_waitcnt lgkmcnt(0)
	v_cndmask_b32_e64 v134, v132, -v132, s[0:1]
	v_mov_b32_e32 v132, v116
	v_mov_b32_e32 v147, v134
	v_pk_mul_f32 v[132:133], v[132:133], v[146:147]
	v_mov_b32_e32 v134, v117
	v_add_f32_e32 v132, v132, v133
	ds_bpermute_b32 v133, v177, v117
	v_cndmask_b32_e64 v132, v116, v132, s[10:11]
	v_mov_b32_e32 v222, v132
	s_waitcnt lgkmcnt(0)
	v_cndmask_b32_e64 v133, v133, -v133, s[0:1]
	v_mov_b32_e32 v149, v133
	v_pk_mul_f32 v[134:135], v[134:135], v[148:149]
	s_nop 0
	v_add_f32_e32 v133, v134, v135
	ds_bpermute_b32 v134, v177, v118
	v_mov_b32_e32 v135, v143
	v_cndmask_b32_e64 v133, v117, v133, s[10:11]
	v_mov_b32_e32 v223, v133
	s_waitcnt lgkmcnt(0)
	v_cndmask_b32_e64 v136, v134, -v134, s[0:1]
	v_mov_b32_e32 v134, v118
	v_mov_b32_e32 v143, v136
	v_pk_mul_f32 v[134:135], v[134:135], v[142:143]
	v_mov_b32_e32 v136, v119
	v_add_f32_e32 v134, v134, v135
	ds_bpermute_b32 v135, v177, v119
	v_cndmask_b32_e64 v134, v118, v134, s[10:11]
	v_mov_b32_e32 v220, v134
	s_waitcnt lgkmcnt(0)
	v_cndmask_b32_e64 v135, v135, -v135, s[0:1]
	v_mov_b32_e32 v145, v135
	v_pk_mul_f32 v[136:137], v[136:137], v[144:145]
	s_nop 0
	v_add_f32_e32 v135, v136, v137
	ds_bpermute_b32 v136, v177, v120
	v_mov_b32_e32 v137, v139
	v_cndmask_b32_e64 v135, v119, v135, s[10:11]
	v_mov_b32_e32 v221, v135
	s_waitcnt lgkmcnt(0)
	v_cndmask_b32_e64 v142, v136, -v136, s[0:1]
	v_mov_b32_e32 v136, v120
	v_mov_b32_e32 v139, v142
	v_pk_mul_f32 v[136:137], v[136:137], v[138:139]
	v_mov_b32_e32 v138, v121
	v_add_f32_e32 v136, v136, v137
	ds_bpermute_b32 v137, v177, v121
	v_mov_b32_e32 v139, v141
	v_cndmask_b32_e64 v136, v120, v136, s[10:11]
	v_mov_b32_e32 v181, v136
	s_waitcnt lgkmcnt(0)
	v_cndmask_b32_e64 v137, v137, -v137, s[0:1]
	v_mov_b32_e32 v141, v137
	v_pk_mul_f32 v[138:139], v[138:139], v[140:141]
	s_nop 0
	v_add_f32_e32 v137, v138, v139
	v_cndmask_b32_e64 v137, v121, v137, s[10:11]
	v_mov_b32_e32 v219, v137
.LBB0_407:
	s_waitcnt vmcnt(7)
	v_add_u32_e32 v138, s33, v164
	v_lshlrev_b32_e32 v178, 2, v138
	v_mov_b32_e32 v179, v163
	v_lshl_add_u64 v[138:139], v[184:185], 0, v[178:179]
	global_store_dwordx4 v[138:139], v[130:133], off offset:512 nt
	global_store_dwordx4 v[138:139], v[134:137], off offset:528 nt
	s_and_saveexec_b64 s[2:3], s[6:7]
	s_xor_b64 s[2:3], exec, s[2:3]
	s_cbranch_execz .LBB0_409
	v_lshl_add_u64 v[134:135], v[174:175], 1, v[182:183]
	v_cvt_pk_bf16_f32 v130, v224, v225
	v_cvt_pk_bf16_f32 v131, v222, v223
	v_cvt_pk_bf16_f32 v132, v220, v221
	v_cvt_pk_bf16_f32 v133, v181, v219
	global_store_dwordx4 v[134:135], v[130:133], off offset:256

; DI void st8f_nt(float* p, const float (&v)[8]) { __builtin_nontemporal_store((v4f){v[0], v[1], v[2], v[3]}, (v4f*)p); __builtin_nontemporal_store((v4f){v[4], v[5], v[6], v[7]}, (v4f*)(p + 4)); }
;     template <int MODE>
;     DI void rows(const pg8::f32x4 (&acc)[2][2][4][2], const pg8::Unit& u, int wr, int wc, int fr, int fq) const {
;     ...
;                     const int col = pn * 256 + bj * 128 + tc0;
;                     if constexpr (MODE <= 1) {
;                         if ((wc & 1) == 0) {
;                             const float sgn = fq == 0 ? -1.f : 1.f;
; #pragma unroll
;                             for (int i = 0; i < 8; ++i) { const float pr = __shfl_xor(v[i], 16); const float r = v[i] * cs[i].x + sgn * pr * cs[i].y; v[i] = fq < 2 ? r : v[i]; }
;                         }
;                         if constexpr (MODE == 0) {
; #pragma unroll
;                             for (int i = 0; i < 8; ++i) v[i] *= QA_SCALE;
;                         }
;                     }
;                     if constexpr (MODE == 1 || MODE == 2) {
;                         const int cs1 = (pn & 3) * 256 + bj * 128 + tc0;
;                         float* dst = row < MP ? out + (MODE == 1 ? O_KP : O_VP) + (size_t)row * 1024 + cs1 : out + (MODE == 1 ? O_KS : O_VS) + (size_t)(row - MP) * 1024 + cs1;
;                         st8f_nt(dst, v);
;     ...
;                     } else if constexpr (MODE == 1 || MODE == 2) {
;                         if (row < MP) {
;                             const int cc = (pn & 3) * 256 + bj * 128 + tc0, hd = cc >> 7;
;                             st8bf((MODE == 1 ? KC : VC) + ((size_t)((row >> 12) * 8 + hd) * SEQ + (row & (SEQ - 1))) * 128 + (cc & 127), v);
;                         } else st8bf(P + (size_t)row * PLD + col, v);
.LBB0_422:
	v_and_b32_e32 v131, 64, v216
	v_xor_b32_e32 v130, 16, v216
	v_add_u32_e32 v131, 64, v131
	v_cmp_lt_i32_e32 vcc, v130, v131
	s_waitcnt vmcnt(10)
	v_mov_b32_e32 v131, v241
	v_mov_b32_e32 v133, v243
	v_cndmask_b32_e32 v130, v216, v130, vcc
	v_lshlrev_b32_e32 v177, 2, v130
	ds_bpermute_b32 v130, v177, v98
	v_mov_b32_e32 v135, v239
	v_mov_b32_e32 v137, v235
	s_waitcnt lgkmcnt(0)
	v_cndmask_b32_e64 v132, v130, -v130, s[0:1]
	v_mov_b32_e32 v130, v98
	v_mov_b32_e32 v241, v132
	v_pk_mul_f32 v[130:131], v[130:131], v[240:241]
	v_mov_b32_e32 v132, v99
	v_add_f32_e32 v130, v130, v131
	ds_bpermute_b32 v131, v177, v99
	v_cndmask_b32_e64 v130, v98, v130, s[10:11]
	v_mov_b32_e32 v224, v130
	s_waitcnt lgkmcnt(0)
	v_cndmask_b32_e64 v131, v131, -v131, s[0:1]
	v_mov_b32_e32 v243, v131
	v_pk_mul_f32 v[132:133], v[132:133], v[242:243]
	s_nop 0
	v_add_f32_e32 v131, v132, v133
	ds_bpermute_b32 v132, v177, v100
	v_mov_b32_e32 v133, v237
	v_cndmask_b32_e64 v131, v99, v131, s[10:11]
	v_mov_b32_e32 v225, v131
	s_waitcnt lgkmcnt(0)
	v_cndmask_b32_e64 v134, v132, -v132, s[0:1]
	v_mov_b32_e32 v132, v100
	v_mov_b32_e32 v237, v134
	v_pk_mul_f32 v[132:133], v[132:133], v[236:237]
	v_mov_b32_e32 v134, v101
	v_add_f32_e32 v132, v132, v133
	ds_bpermute_b32 v133, v177, v101
	v_cndmask_b32_e64 v132, v100, v132, s[10:11]
	v_mov_b32_e32 v222, v132
	s_waitcnt lgkmcnt(0)
	v_cndmask_b32_e64 v133, v133, -v133, s[0:1]
	v_mov_b32_e32 v239, v133
	v_pk_mul_f32 v[134:135], v[134:135], v[238:239]
	s_nop 0
	v_add_f32_e32 v133, v134, v135
	ds_bpermute_b32 v134, v177, v102
	v_mov_b32_e32 v135, v233
	v_cndmask_b32_e64 v133, v101, v133, s[10:11]
	v_mov_b32_e32 v223, v133
	s_waitcnt lgkmcnt(0)
	v_cndmask_b32_e64 v136, v134, -v134, s[0:1]
	v_mov_b32_e32 v134, v102
	v_mov_b32_e32 v233, v136
	v_pk_mul_f32 v[134:135], v[134:135], v[232:233]
	v_mov_b32_e32 v136, v103
	v_add_f32_e32 v134, v134, v135
	ds_bpermute_b32 v135, v177, v103
	v_cndmask_b32_e64 v134, v102, v134, s[10:11]
	v_mov_b32_e32 v220, v134
	s_waitcnt lgkmcnt(0)
	v_cndmask_b32_e64 v135, v135, -v135, s[0:1]
	v_mov_b32_e32 v235, v135
	v_pk_mul_f32 v[136:137], v[136:137], v[234:235]
	s_nop 0
	v_add_f32_e32 v135, v136, v137
	ds_bpermute_b32 v136, v177, v104
	v_mov_b32_e32 v137, v229
	v_cndmask_b32_e64 v135, v103, v135, s[10:11]
	v_mov_b32_e32 v221, v135
	s_waitcnt lgkmcnt(0)
	v_cndmask_b32_e64 v232, v136, -v136, s[0:1]
	v_mov_b32_e32 v136, v104
	v_mov_b32_e32 v229, v232
	v_pk_mul_f32 v[136:137], v[136:137], v[228:229]
	v_mov_b32_e32 v228, v105
	v_add_f32_e32 v136, v136, v137
	ds_bpermute_b32 v137, v177, v105
	v_mov_b32_e32 v229, v231
	v_cndmask_b32_e64 v136, v104, v136, s[10:11]
	v_mov_b32_e32 v181, v136
	s_waitcnt lgkmcnt(0)
	v_cndmask_b32_e64 v137, v137, -v137, s[0:1]
	v_mov_b32_e32 v231, v137
	v_pk_mul_f32 v[228:229], v[228:229], v[230:231]
	s_nop 0
	v_add_f32_e32 v137, v228, v229
	v_cndmask_b32_e64 v137, v105, v137, s[10:11]
	v_mov_b32_e32 v219, v137
.LBB0_423:
	v_mov_b32_e32 v179, v163
	s_waitcnt vmcnt(10)
	v_lshl_add_u64 v[228:229], v[184:185], 0, v[178:179]
	global_store_dwordx4 v[228:229], v[130:133], off offset:512 nt
	global_store_dwordx4 v[228:229], v[134:137], off offset:528 nt
	s_and_saveexec_b64 s[2:3], s[6:7]
	s_xor_b64 s[2:3], exec, s[2:3]
	s_cbranch_execz .LBB0_425
	v_lshl_add_u64 v[134:135], v[174:175], 1, v[182:183]
	v_cvt_pk_bf16_f32 v130, v224, v225
	v_cvt_pk_bf16_f32 v131, v222, v223
	v_cvt_pk_bf16_f32 v132, v220, v221
	v_cvt_pk_bf16_f32 v133, v181, v219
	global_store_dwordx4 v[134:135], v[130:133], off offset:256

; DI void st8f_nt(float* p, const float (&v)[8]) { __builtin_nontemporal_store((v4f){v[0], v[1], v[2], v[3]}, (v4f*)p); __builtin_nontemporal_store((v4f){v[4], v[5], v[6], v[7]}, (v4f*)(p + 4)); }
;     template <int MODE>
;     DI void rows(const pg8::f32x4 (&acc)[2][2][4][2], const pg8::Unit& u, int wr, int wc, int fr, int fq) const {
;     ...
;                     const int col = pn * 256 + bj * 128 + tc0;
;                     if constexpr (MODE <= 1) {
;                         if ((wc & 1) == 0) {
;                             const float sgn = fq == 0 ? -1.f : 1.f;
; #pragma unroll
;                             for (int i = 0; i < 8; ++i) { const float pr = __shfl_xor(v[i], 16); const float r = v[i] * cs[i].x + sgn * pr * cs[i].y; v[i] = fq < 2 ? r : v[i]; }
;                         }
;                         if constexpr (MODE == 0) {
; #pragma unroll
;                             for (int i = 0; i < 8; ++i) v[i] *= QA_SCALE;
;                         }
;                     }
;                     if constexpr (MODE == 1 || MODE == 2) {
;                         const int cs1 = (pn & 3) * 256 + bj * 128 + tc0;
;                         float* dst = row < MP ? out + (MODE == 1 ? O_KP : O_VP) + (size_t)row * 1024 + cs1 : out + (MODE == 1 ? O_KS : O_VS) + (size_t)(row - MP) * 1024 + cs1;
;                         st8f_nt(dst, v);
;     ...
;                     } else if constexpr (MODE == 1 || MODE == 2) {
;                         if (row < MP) {
;                             const int cc = (pn & 3) * 256 + bj * 128 + tc0, hd = cc >> 7;
;                             st8bf((MODE == 1 ? KC : VC) + ((size_t)((row >> 12) * 8 + hd) * SEQ + (row & (SEQ - 1))) * 128 + (cc & 127), v);
;                         } else st8bf(P + (size_t)row * PLD + col, v);
.LBB0_438:
	v_and_b32_e32 v131, 64, v216
	v_xor_b32_e32 v130, 16, v216
	v_add_u32_e32 v131, 64, v131
	v_cmp_lt_i32_e32 vcc, v130, v131
	s_waitcnt vmcnt(10)
	v_mov_b32_e32 v131, v151
	v_mov_b32_e32 v133, v153
	v_cndmask_b32_e32 v130, v216, v130, vcc
	v_lshlrev_b32_e32 v177, 2, v130
	ds_bpermute_b32 v130, v177, v82
	v_mov_b32_e32 v135, v149
	v_mov_b32_e32 v137, v145
	s_waitcnt lgkmcnt(0)
	v_cndmask_b32_e64 v132, v130, -v130, s[0:1]
	v_mov_b32_e32 v130, v82
	v_mov_b32_e32 v151, v132
	v_pk_mul_f32 v[130:131], v[130:131], v[150:151]
	v_mov_b32_e32 v132, v83
	v_add_f32_e32 v130, v130, v131
	ds_bpermute_b32 v131, v177, v83
	v_cndmask_b32_e64 v130, v82, v130, s[10:11]
	v_mov_b32_e32 v224, v130
	s_waitcnt lgkmcnt(0)
	v_cndmask_b32_e64 v131, v131, -v131, s[0:1]
	v_mov_b32_e32 v153, v131
	v_pk_mul_f32 v[132:133], v[132:133], v[152:153]
	s_nop 0
	v_add_f32_e32 v131, v132, v133
	ds_bpermute_b32 v132, v177, v84
	v_mov_b32_e32 v133, v147
	v_cndmask_b32_e64 v131, v83, v131, s[10:11]
	v_mov_b32_e32 v225, v131
	s_waitcnt lgkmcnt(0)
	v_cndmask_b32_e64 v134, v132, -v132, s[0:1]
	v_mov_b32_e32 v132, v84
	v_mov_b32_e32 v147, v134
	v_pk_mul_f32 v[132:133], v[132:133], v[146:147]
	v_mov_b32_e32 v134, v85
	v_add_f32_e32 v132, v132, v133
	ds_bpermute_b32 v133, v177, v85
	v_cndmask_b32_e64 v132, v84, v132, s[10:11]
	v_mov_b32_e32 v222, v132
	s_waitcnt lgkmcnt(0)
	v_cndmask_b32_e64 v133, v133, -v133, s[0:1]
	v_mov_b32_e32 v149, v133
	v_pk_mul_f32 v[134:135], v[134:135], v[148:149]
	s_nop 0
	v_add_f32_e32 v133, v134, v135
	ds_bpermute_b32 v134, v177, v86
	v_mov_b32_e32 v135, v143
	v_cndmask_b32_e64 v133, v85, v133, s[10:11]
	v_mov_b32_e32 v223, v133
	s_waitcnt lgkmcnt(0)
	v_cndmask_b32_e64 v136, v134, -v134, s[0:1]
	v_mov_b32_e32 v134, v86
	v_mov_b32_e32 v143, v136
	v_pk_mul_f32 v[134:135], v[134:135], v[142:143]
	v_mov_b32_e32 v136, v87
	v_add_f32_e32 v134, v134, v135
	ds_bpermute_b32 v135, v177, v87
	v_cndmask_b32_e64 v134, v86, v134, s[10:11]
	v_mov_b32_e32 v220, v134
	s_waitcnt lgkmcnt(0)
	v_cndmask_b32_e64 v135, v135, -v135, s[0:1]
	v_mov_b32_e32 v145, v135
	v_pk_mul_f32 v[136:137], v[136:137], v[144:145]
	s_nop 0
	v_add_f32_e32 v135, v136, v137
	ds_bpermute_b32 v136, v177, v88
	v_mov_b32_e32 v137, v139
	v_cndmask_b32_e64 v135, v87, v135, s[10:11]
	v_mov_b32_e32 v221, v135
	s_waitcnt lgkmcnt(0)
	v_cndmask_b32_e64 v142, v136, -v136, s[0:1]
	v_mov_b32_e32 v136, v88
	v_mov_b32_e32 v139, v142
	v_pk_mul_f32 v[136:137], v[136:137], v[138:139]
	v_mov_b32_e32 v138, v89
	v_add_f32_e32 v136, v136, v137
	ds_bpermute_b32 v137, v177, v89
	v_mov_b32_e32 v139, v141
	v_cndmask_b32_e64 v136, v88, v136, s[10:11]
	v_mov_b32_e32 v181, v136
	s_waitcnt lgkmcnt(0)
	v_cndmask_b32_e64 v137, v137, -v137, s[0:1]
	v_mov_b32_e32 v141, v137
	v_pk_mul_f32 v[138:139], v[138:139], v[140:141]
	s_nop 0
	v_add_f32_e32 v137, v138, v139
	v_cndmask_b32_e64 v137, v89, v137, s[10:11]
	v_mov_b32_e32 v219, v137
.LBB0_439:
	v_mov_b32_e32 v179, v163
	s_waitcnt vmcnt(10)
	v_lshl_add_u64 v[138:139], v[184:185], 0, v[178:179]
	global_store_dwordx4 v[138:139], v[130:133], off offset:512 nt
	global_store_dwordx4 v[138:139], v[134:137], off offset:528 nt
	s_and_saveexec_b64 s[2:3], s[6:7]
	s_xor_b64 s[2:3], exec, s[2:3]
	s_cbranch_execz .LBB0_441
	v_lshl_add_u64 v[134:135], v[174:175], 1, v[182:183]
	v_cvt_pk_bf16_f32 v130, v224, v225
	v_cvt_pk_bf16_f32 v131, v222, v223
	v_cvt_pk_bf16_f32 v132, v220, v221
	v_cvt_pk_bf16_f32 v133, v181, v219
	global_store_dwordx4 v[134:135], v[130:133], off offset:256

; DI void st8f_nt(float* p, const float (&v)[8]) { __builtin_nontemporal_store((v4f){v[0], v[1], v[2], v[3]}, (v4f*)p); __builtin_nontemporal_store((v4f){v[4], v[5], v[6], v[7]}, (v4f*)(p + 4)); }
;     template <int MODE>
;     DI void rows(const pg8::f32x4 (&acc)[2][2][4][2], const pg8::Unit& u, int wr, int wc, int fr, int fq) const {
;     ...
;                     const int col = pn * 256 + bj * 128 + tc0;
;                     if constexpr (MODE <= 1) {
;                         if ((wc & 1) == 0) {
;                             const float sgn = fq == 0 ? -1.f : 1.f;
; #pragma unroll
;                             for (int i = 0; i < 8; ++i) { const float pr = __shfl_xor(v[i], 16); const float r = v[i] * cs[i].x + sgn * pr * cs[i].y; v[i] = fq < 2 ? r : v[i]; }
;                         }
;                         if constexpr (MODE == 0) {
; #pragma unroll
;                             for (int i = 0; i < 8; ++i) v[i] *= QA_SCALE;
;                         }
;                     }
;                     if constexpr (MODE == 1 || MODE == 2) {
;                         const int cs1 = (pn & 3) * 256 + bj * 128 + tc0;
;                         float* dst = row < MP ? out + (MODE == 1 ? O_KP : O_VP) + (size_t)row * 1024 + cs1 : out + (MODE == 1 ? O_KS : O_VS) + (size_t)(row - MP) * 1024 + cs1;
;                         st8f_nt(dst, v);
;     ...
;                     } else if constexpr (MODE == 1 || MODE == 2) {
;                         if (row < MP) {
;                             const int cc = (pn & 3) * 256 + bj * 128 + tc0, hd = cc >> 7;
;                             st8bf((MODE == 1 ? KC : VC) + ((size_t)((row >> 12) * 8 + hd) * SEQ + (row & (SEQ - 1))) * 128 + (cc & 127), v);
;                         } else st8bf(P + (size_t)row * PLD + col, v);
.LBB0_454:
	v_and_b32_e32 v131, 64, v216
	v_xor_b32_e32 v130, 16, v216
	v_add_u32_e32 v131, 64, v131
	v_cmp_lt_i32_e32 vcc, v130, v131
	s_waitcnt vmcnt(10)
	v_mov_b32_e32 v131, v241
	v_mov_b32_e32 v133, v243
	v_cndmask_b32_e32 v130, v216, v130, vcc
	v_lshlrev_b32_e32 v177, 2, v130
	ds_bpermute_b32 v130, v177, v66
	v_mov_b32_e32 v135, v239
	v_mov_b32_e32 v137, v235
	s_waitcnt lgkmcnt(0)
	v_cndmask_b32_e64 v132, v130, -v130, s[0:1]
	v_mov_b32_e32 v130, v66
	v_mov_b32_e32 v241, v132
	v_pk_mul_f32 v[130:131], v[130:131], v[240:241]
	v_mov_b32_e32 v132, v67
	v_add_f32_e32 v130, v130, v131
	ds_bpermute_b32 v131, v177, v67
	v_cndmask_b32_e64 v130, v66, v130, s[10:11]
	v_mov_b32_e32 v223, v130
	s_waitcnt lgkmcnt(0)
	v_cndmask_b32_e64 v131, v131, -v131, s[0:1]
	v_mov_b32_e32 v243, v131
	v_pk_mul_f32 v[132:133], v[132:133], v[242:243]
	s_nop 0
	v_add_f32_e32 v131, v132, v133
	ds_bpermute_b32 v132, v177, v68
	v_mov_b32_e32 v133, v237
	v_cndmask_b32_e64 v131, v67, v131, s[10:11]
	v_mov_b32_e32 v224, v131
	s_waitcnt lgkmcnt(0)
	v_cndmask_b32_e64 v134, v132, -v132, s[0:1]
	v_mov_b32_e32 v132, v68
	v_mov_b32_e32 v237, v134
	v_pk_mul_f32 v[132:133], v[132:133], v[236:237]
	v_mov_b32_e32 v134, v69
	v_add_f32_e32 v132, v132, v133
	ds_bpermute_b32 v133, v177, v69
	v_cndmask_b32_e64 v132, v68, v132, s[10:11]
	v_mov_b32_e32 v221, v132
	s_waitcnt lgkmcnt(0)
	v_cndmask_b32_e64 v133, v133, -v133, s[0:1]
	v_mov_b32_e32 v239, v133
	v_pk_mul_f32 v[134:135], v[134:135], v[238:239]
	s_nop 0
	v_add_f32_e32 v133, v134, v135
	ds_bpermute_b32 v134, v177, v70
	v_mov_b32_e32 v135, v233
	v_cndmask_b32_e64 v133, v69, v133, s[10:11]
	v_mov_b32_e32 v222, v133
	s_waitcnt lgkmcnt(0)
	v_cndmask_b32_e64 v136, v134, -v134, s[0:1]
	v_mov_b32_e32 v134, v70
	v_mov_b32_e32 v233, v136
	v_pk_mul_f32 v[134:135], v[134:135], v[232:233]
	v_mov_b32_e32 v136, v71
	v_add_f32_e32 v134, v134, v135
	ds_bpermute_b32 v135, v177, v71
	v_cndmask_b32_e64 v134, v70, v134, s[10:11]
	v_mov_b32_e32 v219, v134
	s_waitcnt lgkmcnt(0)
	v_cndmask_b32_e64 v135, v135, -v135, s[0:1]
	v_mov_b32_e32 v235, v135
	v_pk_mul_f32 v[136:137], v[136:137], v[234:235]
	s_nop 0
	v_add_f32_e32 v135, v136, v137
	ds_bpermute_b32 v136, v177, v72
	v_mov_b32_e32 v137, v229
	v_cndmask_b32_e64 v135, v71, v135, s[10:11]
	v_mov_b32_e32 v220, v135
	s_waitcnt lgkmcnt(0)
	v_cndmask_b32_e64 v232, v136, -v136, s[0:1]
	v_mov_b32_e32 v136, v72
	v_mov_b32_e32 v229, v232
	v_pk_mul_f32 v[136:137], v[136:137], v[228:229]
	v_mov_b32_e32 v228, v73
	v_add_f32_e32 v136, v136, v137
	ds_bpermute_b32 v137, v177, v73
	v_mov_b32_e32 v229, v231
	v_cndmask_b32_e64 v136, v72, v136, s[10:11]
	v_mov_b32_e32 v186, v136
	s_waitcnt lgkmcnt(0)
	v_cndmask_b32_e64 v137, v137, -v137, s[0:1]
	v_mov_b32_e32 v231, v137
	v_pk_mul_f32 v[228:229], v[228:229], v[230:231]
	s_nop 0
	v_add_f32_e32 v137, v228, v229
	v_cndmask_b32_e64 v137, v73, v137, s[10:11]
	v_mov_b32_e32 v187, v137
.LBB0_455:
	v_mov_b32_e32 v179, v163
	s_waitcnt vmcnt(10)
	v_lshl_add_u64 v[228:229], v[182:183], 0, v[178:179]
	global_store_dwordx4 v[228:229], v[130:133], off offset:512 nt
	global_store_dwordx4 v[228:229], v[134:137], off offset:528 nt
	s_and_saveexec_b64 s[2:3], s[6:7]
	s_xor_b64 s[2:3], exec, s[2:3]
	s_cbranch_execz .LBB0_457
	v_lshl_add_u64 v[134:135], v[174:175], 1, v[180:181]
	v_cvt_pk_bf16_f32 v130, v223, v224
	v_cvt_pk_bf16_f32 v131, v221, v222
	v_cvt_pk_bf16_f32 v132, v219, v220
	v_cvt_pk_bf16_f32 v133, v186, v187
	global_store_dwordx4 v[134:135], v[130:133], off offset:256

;     template <int MODE>
;     DI void rows(const pg8::f32x4 (&acc)[2][2][4][2], const pg8::Unit& u, int wr, int wc, int fr, int fq) const {
;     ...
;                 for (int bj = 0; bj < 2; ++bj) {
;                     float v[8];
; #pragma unroll
;                     for (int i = 0; i < 4; ++i) { v[i] = acc[ai][bj][m][0][i]; v[4 + i] = acc[ai][bj][m][1][i]; }
;                     const int col = pn * 256 + bj * 128 + tc0;
;                     if constexpr (MODE <= 1) {
;                         if ((wc & 1) == 0) {
;                             const float sgn = fq == 0 ? -1.f : 1.f;
; #pragma unroll
;                             for (int i = 0; i < 8; ++i) { const float pr = __shfl_xor(v[i], 16); const float r = v[i] * cs[i].x + sgn * pr * cs[i].y; v[i] = fq < 2 ? r : v[i]; }
;                         }
.LBB0_470:
	v_and_b32_e32 v131, 64, v216
	v_xor_b32_e32 v130, 16, v216
	v_add_u32_e32 v131, 64, v131
	v_cmp_lt_i32_e32 vcc, v130, v131
	s_waitcnt vmcnt(10)
	v_mov_b32_e32 v131, v151
	v_mov_b32_e32 v133, v153
	v_cndmask_b32_e32 v130, v216, v130, vcc
	v_lshlrev_b32_e32 v177, 2, v130
	ds_bpermute_b32 v130, v177, v50
	v_mov_b32_e32 v135, v149
	v_mov_b32_e32 v137, v145
	s_waitcnt lgkmcnt(0)
	v_cndmask_b32_e64 v132, v130, -v130, s[0:1]
	v_mov_b32_e32 v130, v50
	v_mov_b32_e32 v151, v132
	v_pk_mul_f32 v[130:131], v[130:131], v[150:151]
	v_mov_b32_e32 v132, v51
	v_add_f32_e32 v130, v130, v131
	ds_bpermute_b32 v131, v177, v51
	v_cndmask_b32_e64 v130, v50, v130, s[10:11]
	v_mov_b32_e32 v224, v130
	s_waitcnt lgkmcnt(0)
	v_cndmask_b32_e64 v131, v131, -v131, s[0:1]
	v_mov_b32_e32 v153, v131
	v_pk_mul_f32 v[132:133], v[132:133], v[152:153]
	s_nop 0
	v_add_f32_e32 v131, v132, v133
	ds_bpermute_b32 v132, v177, v52
	v_mov_b32_e32 v133, v147
	v_cndmask_b32_e64 v131, v51, v131, s[10:11]
	v_mov_b32_e32 v225, v131
	s_waitcnt lgkmcnt(0)
	v_cndmask_b32_e64 v134, v132, -v132, s[0:1]
	v_mov_b32_e32 v132, v52
	v_mov_b32_e32 v147, v134
	v_pk_mul_f32 v[132:133], v[132:133], v[146:147]
	v_mov_b32_e32 v134, v53
	v_add_f32_e32 v132, v132, v133
	ds_bpermute_b32 v133, v177, v53
	v_cndmask_b32_e64 v132, v52, v132, s[10:11]
	v_mov_b32_e32 v222, v132
	s_waitcnt lgkmcnt(0)
	v_cndmask_b32_e64 v133, v133, -v133, s[0:1]
	v_mov_b32_e32 v149, v133
	v_pk_mul_f32 v[134:135], v[134:135], v[148:149]
	s_nop 0
	v_add_f32_e32 v133, v134, v135
	ds_bpermute_b32 v134, v177, v54
	v_mov_b32_e32 v135, v143
	v_cndmask_b32_e64 v133, v53, v133, s[10:11]
	v_mov_b32_e32 v223, v133
	s_waitcnt lgkmcnt(0)
	v_cndmask_b32_e64 v136, v134, -v134, s[0:1]
	v_mov_b32_e32 v134, v54
	v_mov_b32_e32 v143, v136
	v_pk_mul_f32 v[134:135], v[134:135], v[142:143]
	v_mov_b32_e32 v136, v55
	v_add_f32_e32 v134, v134, v135
	ds_bpermute_b32 v135, v177, v55
	v_cndmask_b32_e64 v134, v54, v134, s[10:11]
	v_mov_b32_e32 v220, v134
	s_waitcnt lgkmcnt(0)
	v_cndmask_b32_e64 v135, v135, -v135, s[0:1]
	v_mov_b32_e32 v145, v135
	v_pk_mul_f32 v[136:137], v[136:137], v[144:145]
	s_nop 0
	v_add_f32_e32 v135, v136, v137
	ds_bpermute_b32 v136, v177, v56
	v_mov_b32_e32 v137, v139
	v_cndmask_b32_e64 v135, v55, v135, s[10:11]
	v_mov_b32_e32 v221, v135
	s_waitcnt lgkmcnt(0)
	v_cndmask_b32_e64 v142, v136, -v136, s[0:1]
	v_mov_b32_e32 v136, v56
	v_mov_b32_e32 v139, v142
	v_pk_mul_f32 v[136:137], v[136:137], v[138:139]
	v_mov_b32_e32 v138, v57
	v_add_f32_e32 v136, v136, v137
	ds_bpermute_b32 v137, v177, v57
	v_mov_b32_e32 v139, v141
	v_cndmask_b32_e64 v136, v56, v136, s[10:11]
	v_mov_b32_e32 v181, v136
	s_waitcnt lgkmcnt(0)
	v_cndmask_b32_e64 v137, v137, -v137, s[0:1]
	v_mov_b32_e32 v141, v137
	v_pk_mul_f32 v[138:139], v[138:139], v[140:141]
	s_nop 0
	v_add_f32_e32 v137, v138, v139
	v_cndmask_b32_e64 v137, v57, v137, s[10:11]
	v_mov_b32_e32 v219, v137

;     template <int MODE>
;     DI void rows(const pg8::f32x4 (&acc)[2][2][4][2], const pg8::Unit& u, int wr, int wc, int fr, int fq) const {
;     ...
;                 for (int bj = 0; bj < 2; ++bj) {
;                     float v[8];
; #pragma unroll
;                     for (int i = 0; i < 4; ++i) { v[i] = acc[ai][bj][m][0][i]; v[4 + i] = acc[ai][bj][m][1][i]; }
;                     const int col = pn * 256 + bj * 128 + tc0;
;                     if constexpr (MODE <= 1) {
;                         if ((wc & 1) == 0) {
;                             const float sgn = fq == 0 ? -1.f : 1.f;
; #pragma unroll
;                             for (int i = 0; i < 8; ++i) { const float pr = __shfl_xor(v[i], 16); const float r = v[i] * cs[i].x + sgn * pr * cs[i].y; v[i] = fq < 2 ? r : v[i]; }
;                         }
.LBB0_486:
	v_and_b32_e32 v131, 64, v216
	v_xor_b32_e32 v130, 16, v216
	v_add_u32_e32 v131, 64, v131
	v_cmp_lt_i32_e32 vcc, v130, v131
	s_waitcnt vmcnt(10)
	v_mov_b32_e32 v131, v241
	v_mov_b32_e32 v133, v243
	v_cndmask_b32_e32 v130, v216, v130, vcc
	v_lshlrev_b32_e32 v177, 2, v130
	ds_bpermute_b32 v130, v177, v34
	v_mov_b32_e32 v135, v239
	v_mov_b32_e32 v137, v235
	s_waitcnt lgkmcnt(0)
	v_cndmask_b32_e64 v132, v130, -v130, s[0:1]
	v_mov_b32_e32 v130, v34
	v_mov_b32_e32 v241, v132
	v_pk_mul_f32 v[130:131], v[130:131], v[240:241]
	v_mov_b32_e32 v132, v35
	v_add_f32_e32 v130, v130, v131
	ds_bpermute_b32 v131, v177, v35
	v_cndmask_b32_e64 v130, v34, v130, s[10:11]
	v_mov_b32_e32 v224, v130
	s_waitcnt lgkmcnt(0)
	v_cndmask_b32_e64 v131, v131, -v131, s[0:1]
	v_mov_b32_e32 v243, v131
	v_pk_mul_f32 v[132:133], v[132:133], v[242:243]
	s_nop 0
	v_add_f32_e32 v131, v132, v133
	ds_bpermute_b32 v132, v177, v36
	v_mov_b32_e32 v133, v237
	v_cndmask_b32_e64 v131, v35, v131, s[10:11]
	v_mov_b32_e32 v225, v131
	s_waitcnt lgkmcnt(0)
	v_cndmask_b32_e64 v134, v132, -v132, s[0:1]
	v_mov_b32_e32 v132, v36
	v_mov_b32_e32 v237, v134
	v_pk_mul_f32 v[132:133], v[132:133], v[236:237]
	v_mov_b32_e32 v134, v37
	v_add_f32_e32 v132, v132, v133
	ds_bpermute_b32 v133, v177, v37
	v_cndmask_b32_e64 v132, v36, v132, s[10:11]
	v_mov_b32_e32 v222, v132
	s_waitcnt lgkmcnt(0)
	v_cndmask_b32_e64 v133, v133, -v133, s[0:1]
	v_mov_b32_e32 v239, v133
	v_pk_mul_f32 v[134:135], v[134:135], v[238:239]
	s_nop 0
	v_add_f32_e32 v133, v134, v135
	ds_bpermute_b32 v134, v177, v38
	v_mov_b32_e32 v135, v233
	v_cndmask_b32_e64 v133, v37, v133, s[10:11]
	v_mov_b32_e32 v223, v133
	s_waitcnt lgkmcnt(0)
	v_cndmask_b32_e64 v136, v134, -v134, s[0:1]
	v_mov_b32_e32 v134, v38
	v_mov_b32_e32 v233, v136
	v_pk_mul_f32 v[134:135], v[134:135], v[232:233]
	v_mov_b32_e32 v136, v39
	v_add_f32_e32 v134, v134, v135
	ds_bpermute_b32 v135, v177, v39
	v_cndmask_b32_e64 v134, v38, v134, s[10:11]
	v_mov_b32_e32 v220, v134
	s_waitcnt lgkmcnt(0)
	v_cndmask_b32_e64 v135, v135, -v135, s[0:1]
	v_mov_b32_e32 v235, v135
	v_pk_mul_f32 v[136:137], v[136:137], v[234:235]
	s_nop 0
	v_add_f32_e32 v135, v136, v137
	ds_bpermute_b32 v136, v177, v40
	v_mov_b32_e32 v137, v229
	v_cndmask_b32_e64 v135, v39, v135, s[10:11]
	v_mov_b32_e32 v221, v135
	s_waitcnt lgkmcnt(0)
	v_cndmask_b32_e64 v232, v136, -v136, s[0:1]
	v_mov_b32_e32 v136, v40
	v_mov_b32_e32 v229, v232
	v_pk_mul_f32 v[136:137], v[136:137], v[228:229]
	v_mov_b32_e32 v228, v41
	v_add_f32_e32 v136, v136, v137
	ds_bpermute_b32 v137, v177, v41
	v_mov_b32_e32 v229, v231
	v_cndmask_b32_e64 v136, v40, v136, s[10:11]
	v_mov_b32_e32 v181, v136
	s_waitcnt lgkmcnt(0)
	v_cndmask_b32_e64 v137, v137, -v137, s[0:1]
	v_mov_b32_e32 v231, v137
	v_pk_mul_f32 v[228:229], v[228:229], v[230:231]
	s_nop 0
	v_add_f32_e32 v137, v228, v229
	v_cndmask_b32_e64 v137, v41, v137, s[10:11]
	v_mov_b32_e32 v219, v137

;     template <int MODE>
;     DI void rows(const pg8::f32x4 (&acc)[2][2][4][2], const pg8::Unit& u, int wr, int wc, int fr, int fq) const {
;     ...
;                 for (int bj = 0; bj < 2; ++bj) {
;                     float v[8];
; #pragma unroll
;                     for (int i = 0; i < 4; ++i) { v[i] = acc[ai][bj][m][0][i]; v[4 + i] = acc[ai][bj][m][1][i]; }
;                     const int col = pn * 256 + bj * 128 + tc0;
;                     if constexpr (MODE <= 1) {
;                         if ((wc & 1) == 0) {
;                             const float sgn = fq == 0 ? -1.f : 1.f;
; #pragma unroll
;                             for (int i = 0; i < 8; ++i) { const float pr = __shfl_xor(v[i], 16); const float r = v[i] * cs[i].x + sgn * pr * cs[i].y; v[i] = fq < 2 ? r : v[i]; }
;                         }
.LBB0_502:
	v_and_b32_e32 v131, 64, v216
	v_xor_b32_e32 v130, 16, v216
	v_add_u32_e32 v131, 64, v131
	v_cmp_lt_i32_e32 vcc, v130, v131
	s_waitcnt vmcnt(10)
	v_mov_b32_e32 v131, v151
	v_mov_b32_e32 v133, v153
	v_cndmask_b32_e32 v130, v216, v130, vcc
	v_lshlrev_b32_e32 v177, 2, v130
	ds_bpermute_b32 v130, v177, v18
	v_mov_b32_e32 v135, v149
	v_mov_b32_e32 v137, v145
	s_waitcnt lgkmcnt(0)
	v_cndmask_b32_e64 v132, v130, -v130, s[0:1]
	v_mov_b32_e32 v130, v18
	v_mov_b32_e32 v151, v132
	v_pk_mul_f32 v[130:131], v[130:131], v[150:151]
	v_mov_b32_e32 v132, v19
	v_add_f32_e32 v130, v130, v131
	ds_bpermute_b32 v131, v177, v19
	v_cndmask_b32_e64 v130, v18, v130, s[10:11]
	v_mov_b32_e32 v224, v130
	s_waitcnt lgkmcnt(0)
	v_cndmask_b32_e64 v131, v131, -v131, s[0:1]
	v_mov_b32_e32 v153, v131
	v_pk_mul_f32 v[132:133], v[132:133], v[152:153]
	s_nop 0
	v_add_f32_e32 v131, v132, v133
	ds_bpermute_b32 v132, v177, v20
	v_mov_b32_e32 v133, v147
	v_cndmask_b32_e64 v131, v19, v131, s[10:11]
	v_mov_b32_e32 v225, v131
	s_waitcnt lgkmcnt(0)
	v_cndmask_b32_e64 v134, v132, -v132, s[0:1]
	v_mov_b32_e32 v132, v20
	v_mov_b32_e32 v147, v134
	v_pk_mul_f32 v[132:133], v[132:133], v[146:147]
	v_mov_b32_e32 v134, v21
	v_add_f32_e32 v132, v132, v133
	ds_bpermute_b32 v133, v177, v21
	v_cndmask_b32_e64 v132, v20, v132, s[10:11]
	v_mov_b32_e32 v222, v132
	s_waitcnt lgkmcnt(0)
	v_cndmask_b32_e64 v133, v133, -v133, s[0:1]
	v_mov_b32_e32 v149, v133
	v_pk_mul_f32 v[134:135], v[134:135], v[148:149]
	s_nop 0
	v_add_f32_e32 v133, v134, v135
	ds_bpermute_b32 v134, v177, v22
	v_mov_b32_e32 v135, v143
	v_cndmask_b32_e64 v133, v21, v133, s[10:11]
	v_mov_b32_e32 v223, v133
	s_waitcnt lgkmcnt(0)
	v_cndmask_b32_e64 v136, v134, -v134, s[0:1]
	v_mov_b32_e32 v134, v22
	v_mov_b32_e32 v143, v136
	v_pk_mul_f32 v[134:135], v[134:135], v[142:143]
	v_mov_b32_e32 v136, v23
	v_add_f32_e32 v134, v134, v135
	ds_bpermute_b32 v135, v177, v23
	v_cndmask_b32_e64 v134, v22, v134, s[10:11]
	v_mov_b32_e32 v220, v134
	s_waitcnt lgkmcnt(0)
	v_cndmask_b32_e64 v135, v135, -v135, s[0:1]
	v_mov_b32_e32 v145, v135
	v_pk_mul_f32 v[136:137], v[136:137], v[144:145]
	s_nop 0
	v_add_f32_e32 v135, v136, v137
	ds_bpermute_b32 v136, v177, v24
	v_mov_b32_e32 v137, v139
	v_cndmask_b32_e64 v135, v23, v135, s[10:11]
	v_mov_b32_e32 v221, v135
	s_waitcnt lgkmcnt(0)
	v_cndmask_b32_e64 v142, v136, -v136, s[0:1]
	v_mov_b32_e32 v136, v24
	v_mov_b32_e32 v139, v142
	v_pk_mul_f32 v[136:137], v[136:137], v[138:139]
	v_mov_b32_e32 v138, v25
	v_add_f32_e32 v136, v136, v137
	ds_bpermute_b32 v137, v177, v25
	v_mov_b32_e32 v139, v141
	v_cndmask_b32_e64 v136, v24, v136, s[10:11]
	v_mov_b32_e32 v181, v136
	s_waitcnt lgkmcnt(0)
	v_cndmask_b32_e64 v137, v137, -v137, s[0:1]
	v_mov_b32_e32 v141, v137
	v_pk_mul_f32 v[138:139], v[138:139], v[140:141]
	s_nop 0
	v_add_f32_e32 v137, v138, v139
	v_cndmask_b32_e64 v137, v25, v137, s[10:11]
	v_mov_b32_e32 v219, v137

; DI void st8f_nt(float* p, const float (&v)[8]) { __builtin_nontemporal_store((v4f){v[0], v[1], v[2], v[3]}, (v4f*)p); __builtin_nontemporal_store((v4f){v[4], v[5], v[6], v[7]}, (v4f*)(p + 4)); }
;     template <int MODE>
;     DI void rows(const pg8::f32x4 (&acc)[2][2][4][2], const pg8::Unit& u, int wr, int wc, int fr, int fq) const {
;     ...
;                     const int col = pn * 256 + bj * 128 + tc0;
;                     if constexpr (MODE <= 1) {
;                         if ((wc & 1) == 0) {
;                             const float sgn = fq == 0 ? -1.f : 1.f;
; #pragma unroll
;                             for (int i = 0; i < 8; ++i) { const float pr = __shfl_xor(v[i], 16); const float r = v[i] * cs[i].x + sgn * pr * cs[i].y; v[i] = fq < 2 ? r : v[i]; }
;                         }
;                         if constexpr (MODE == 0) {
; #pragma unroll
;                             for (int i = 0; i < 8; ++i) v[i] *= QA_SCALE;
;                         }
;                     }
;                     if constexpr (MODE == 1 || MODE == 2) {
;                         const int cs1 = (pn & 3) * 256 + bj * 128 + tc0;
;                         float* dst = row < MP ? out + (MODE == 1 ? O_KP : O_VP) + (size_t)row * 1024 + cs1 : out + (MODE == 1 ? O_KS : O_VS) + (size_t)(row - MP) * 1024 + cs1;
;                         st8f_nt(dst, v);
;     ...
;                     } else if constexpr (MODE == 1 || MODE == 2) {
;                         if (row < MP) {
;                             const int cc = (pn & 3) * 256 + bj * 128 + tc0, hd = cc >> 7;
;                             st8bf((MODE == 1 ? KC : VC) + ((size_t)((row >> 12) * 8 + hd) * SEQ + (row & (SEQ - 1))) * 128 + (cc & 127), v);
;                         } else st8bf(P + (size_t)row * PLD + col, v);
.LBB0_518:
	v_and_b32_e32 v131, 64, v216
	v_xor_b32_e32 v130, 16, v216
	v_add_u32_e32 v131, 64, v131
	v_cmp_lt_i32_e32 vcc, v130, v131
	s_waitcnt vmcnt(6)
	v_mov_b32_e32 v131, v241
	v_mov_b32_e32 v133, v243
	v_cndmask_b32_e32 v130, v216, v130, vcc
	v_lshlrev_b32_e32 v177, 2, v130
	ds_bpermute_b32 v130, v177, v2
	v_mov_b32_e32 v135, v239
	v_mov_b32_e32 v137, v235
	s_waitcnt lgkmcnt(0)
	v_cndmask_b32_e64 v132, v130, -v130, s[0:1]
	v_mov_b32_e32 v130, v2
	v_mov_b32_e32 v241, v132
	v_pk_mul_f32 v[130:131], v[130:131], v[240:241]
	v_mov_b32_e32 v132, v3
	v_add_f32_e32 v130, v130, v131
	ds_bpermute_b32 v131, v177, v3
	v_cndmask_b32_e64 v130, v2, v130, s[10:11]
	v_mov_b32_e32 v221, v130
	s_waitcnt lgkmcnt(0)
	v_cndmask_b32_e64 v131, v131, -v131, s[0:1]
	v_mov_b32_e32 v243, v131
	v_pk_mul_f32 v[132:133], v[132:133], v[242:243]
	s_nop 0
	v_add_f32_e32 v131, v132, v133
	ds_bpermute_b32 v132, v177, v4
	v_mov_b32_e32 v133, v237
	v_cndmask_b32_e64 v131, v3, v131, s[10:11]
	v_mov_b32_e32 v222, v131
	s_waitcnt lgkmcnt(0)
	v_cndmask_b32_e64 v134, v132, -v132, s[0:1]
	v_mov_b32_e32 v132, v4
	v_mov_b32_e32 v237, v134
	v_pk_mul_f32 v[132:133], v[132:133], v[236:237]
	v_mov_b32_e32 v134, v5
	v_add_f32_e32 v132, v132, v133
	ds_bpermute_b32 v133, v177, v5
	v_cndmask_b32_e64 v132, v4, v132, s[10:11]
	v_mov_b32_e32 v219, v132
	s_waitcnt lgkmcnt(0)
	v_cndmask_b32_e64 v133, v133, -v133, s[0:1]
	v_mov_b32_e32 v239, v133
	v_pk_mul_f32 v[134:135], v[134:135], v[238:239]
	s_nop 0
	v_add_f32_e32 v133, v134, v135
	ds_bpermute_b32 v134, v177, v6
	v_mov_b32_e32 v135, v233
	v_cndmask_b32_e64 v133, v5, v133, s[10:11]
	v_mov_b32_e32 v220, v133
	s_waitcnt lgkmcnt(0)
	v_cndmask_b32_e64 v136, v134, -v134, s[0:1]
	v_mov_b32_e32 v134, v6
	v_mov_b32_e32 v233, v136
	v_pk_mul_f32 v[134:135], v[134:135], v[232:233]
	v_mov_b32_e32 v136, v7
	v_add_f32_e32 v134, v134, v135
	ds_bpermute_b32 v135, v177, v7
	v_cndmask_b32_e64 v134, v6, v134, s[10:11]
	v_mov_b32_e32 v186, v134
	s_waitcnt lgkmcnt(0)
	v_cndmask_b32_e64 v135, v135, -v135, s[0:1]
	v_mov_b32_e32 v235, v135
	v_pk_mul_f32 v[136:137], v[136:137], v[234:235]
	s_nop 0
	v_add_f32_e32 v135, v136, v137
	ds_bpermute_b32 v136, v177, v8
	v_mov_b32_e32 v137, v229
	v_cndmask_b32_e64 v135, v7, v135, s[10:11]
	v_mov_b32_e32 v187, v135
	s_waitcnt lgkmcnt(0)
	v_cndmask_b32_e64 v232, v136, -v136, s[0:1]
	v_mov_b32_e32 v136, v8
	v_mov_b32_e32 v229, v232
	v_pk_mul_f32 v[136:137], v[136:137], v[228:229]
	v_mov_b32_e32 v228, v9
	v_add_f32_e32 v136, v136, v137
	ds_bpermute_b32 v137, v177, v9
	v_mov_b32_e32 v229, v231
	v_cndmask_b32_e64 v136, v8, v136, s[10:11]
	v_mov_b32_e32 v184, v136
	s_waitcnt lgkmcnt(0)
	v_cndmask_b32_e64 v137, v137, -v137, s[0:1]
	v_mov_b32_e32 v231, v137
	v_pk_mul_f32 v[228:229], v[228:229], v[230:231]
	s_nop 0
	v_add_f32_e32 v137, v228, v229
	v_cndmask_b32_e64 v137, v9, v137, s[10:11]
	v_mov_b32_e32 v185, v137
.LBB0_519:
	v_mov_b32_e32 v179, v163
	s_waitcnt vmcnt(6)
	v_lshl_add_u64 v[228:229], v[182:183], 0, v[178:179]
	global_store_dwordx4 v[228:229], v[130:133], off offset:512 nt
	global_store_dwordx4 v[228:229], v[134:137], off offset:528 nt
	s_and_saveexec_b64 s[2:3], s[6:7]
	s_xor_b64 s[2:3], exec, s[2:3]
	s_cbranch_execz .LBB0_521
	v_lshl_add_u64 v[134:135], v[174:175], 1, v[180:181]
	v_cvt_pk_bf16_f32 v130, v221, v222
	v_cvt_pk_bf16_f32 v131, v219, v220
	v_cvt_pk_bf16_f32 v132, v186, v187
	v_cvt_pk_bf16_f32 v133, v184, v185
	global_store_dwordx4 v[134:135], v[130:133], off offset:256
